# Fourier context item (phase 6): K loop unrolled, all twiddle-fragment loads issued up front with counted waits (was ~8 exposed L2 round trips per output chunk); on top of v54
# speedup vs baseline: 1.0005x; 1.0005x over previous
.LBB0_591:
	v_mov_b32_e32 v0, 0
	s_mov_b32 s10, 0
	v_mov_b64_e32 v[26:27], v[24:25]
	v_mov_b32_e32 v1, v0
	v_mov_b32_e32 v2, v0
	v_mov_b32_e32 v3, v0
	v_mov_b32_e32 v12, v0
	v_mov_b32_e32 v13, v0
	v_mov_b32_e32 v14, v0
	v_mov_b32_e32 v15, v0
	v_mov_b32_e32 v8, v0
	v_mov_b32_e32 v9, v0
	v_mov_b32_e32 v10, v0
	v_mov_b32_e32 v11, v0
	v_mov_b32_e32 v4, v0
	v_mov_b32_e32 v5, v0
	v_mov_b32_e32 v6, v0
	v_mov_b32_e32 v7, v0
	global_load_dwordx4 v[60:63], v[26:27], off offset:-128
	global_load_dwordx4 v[70:73], v[26:27], off offset:-64
	global_load_dwordx4 v[74:77], v[26:27], off
	global_load_dwordx4 v[78:81], v[26:27], off offset:64
	v_lshl_add_u64 v[26:27], v[26:27], 0, s[0:1]
	global_load_dwordx4 v[82:85], v[26:27], off offset:-128
	global_load_dwordx4 v[86:89], v[26:27], off offset:-64
	global_load_dwordx4 v[90:93], v[26:27], off
	global_load_dwordx4 v[94:97], v[26:27], off offset:64
	v_lshl_add_u64 v[26:27], v[26:27], 0, s[0:1]
	global_load_dwordx4 v[110:113], v[26:27], off offset:-128
	global_load_dwordx4 v[114:117], v[26:27], off offset:-64
	global_load_dwordx4 v[122:125], v[26:27], off
	global_load_dwordx4 v[126:129], v[26:27], off offset:64
	v_lshl_add_u64 v[26:27], v[26:27], 0, s[0:1]
	global_load_dwordx4 v[130:133], v[26:27], off offset:-128
	global_load_dwordx4 v[134:137], v[26:27], off offset:-64
	global_load_dwordx4 v[138:141], v[26:27], off
	v_mov_b32_e32 v58, v28
	ds_read_b128 v[38:41], v58
	ds_read_b128 v[42:45], v58 offset:64
	s_waitcnt vmcnt(14) lgkmcnt(1)
	v_mfma_f32_16x16x32_bf16 v[12:15], v[38:41], v[60:63], v[12:15]
	ds_read_b128 v[38:41], v58 offset:16640
	ds_read_b128 v[46:49], v58 offset:16704
	s_waitcnt lgkmcnt(1)
	v_mfma_f32_16x16x32_bf16 v[8:11], v[38:41], v[60:63], v[8:11]
	ds_read_b128 v[38:41], v58 offset:33280
	ds_read_b128 v[50:53], v58 offset:33344
	s_waitcnt lgkmcnt(1)
	v_mfma_f32_16x16x32_bf16 v[4:7], v[38:41], v[60:63], v[4:7]
	ds_read_b128 v[38:41], v58 offset:49920
	ds_read_b128 v[54:57], v58 offset:49984
	s_waitcnt lgkmcnt(1)
	v_mfma_f32_16x16x32_bf16 v[0:3], v[38:41], v[60:63], v[0:3]
	global_load_dwordx4 v[60:63], v[26:27], off offset:64
	s_waitcnt vmcnt(14)
	v_mfma_f32_16x16x32_bf16 v[12:15], v[42:45], v[70:73], v[12:15]
	v_mfma_f32_16x16x32_bf16 v[8:11], v[46:49], v[70:73], v[8:11]
	v_mfma_f32_16x16x32_bf16 v[4:7], v[50:53], v[70:73], v[4:7]
	s_waitcnt lgkmcnt(0)
	v_mfma_f32_16x16x32_bf16 v[0:3], v[54:57], v[70:73], v[0:3]
	ds_read_b128 v[34:37], v58 offset:128
	ds_read_b128 v[42:45], v58 offset:192
	s_waitcnt vmcnt(13) lgkmcnt(1)
	v_mfma_f32_16x16x32_bf16 v[12:15], v[34:37], v[74:77], v[12:15]
	ds_read_b128 v[34:37], v58 offset:16768
	ds_read_b128 v[46:49], v58 offset:16832
	s_waitcnt lgkmcnt(1)
	v_mfma_f32_16x16x32_bf16 v[8:11], v[34:37], v[74:77], v[8:11]
	ds_read_b128 v[34:37], v58 offset:33408
	ds_read_b128 v[50:53], v58 offset:33472
	s_waitcnt lgkmcnt(1)
	v_mfma_f32_16x16x32_bf16 v[4:7], v[34:37], v[74:77], v[4:7]
	ds_read_b128 v[34:37], v58 offset:50048
	ds_read_b128 v[54:57], v58 offset:50112
	s_waitcnt lgkmcnt(1)
	v_mfma_f32_16x16x32_bf16 v[0:3], v[34:37], v[74:77], v[0:3]
	s_waitcnt vmcnt(12)
	v_mfma_f32_16x16x32_bf16 v[12:15], v[42:45], v[78:81], v[12:15]
	v_mfma_f32_16x16x32_bf16 v[8:11], v[46:49], v[78:81], v[8:11]
	v_mfma_f32_16x16x32_bf16 v[4:7], v[50:53], v[78:81], v[4:7]
	s_waitcnt lgkmcnt(0)
	v_mfma_f32_16x16x32_bf16 v[0:3], v[54:57], v[78:81], v[0:3]
	v_add_u32_e32 v58, 0x100, v28
	ds_read_b128 v[38:41], v58
	ds_read_b128 v[42:45], v58 offset:64
	s_waitcnt vmcnt(11) lgkmcnt(1)
	v_mfma_f32_16x16x32_bf16 v[12:15], v[38:41], v[82:85], v[12:15]
	ds_read_b128 v[38:41], v58 offset:16640
	ds_read_b128 v[46:49], v58 offset:16704
	s_waitcnt lgkmcnt(1)
	v_mfma_f32_16x16x32_bf16 v[8:11], v[38:41], v[82:85], v[8:11]
	ds_read_b128 v[38:41], v58 offset:33280
	ds_read_b128 v[50:53], v58 offset:33344
	s_waitcnt lgkmcnt(1)
	v_mfma_f32_16x16x32_bf16 v[4:7], v[38:41], v[82:85], v[4:7]
	ds_read_b128 v[38:41], v58 offset:49920
	ds_read_b128 v[54:57], v58 offset:49984
	s_waitcnt lgkmcnt(1)
	v_mfma_f32_16x16x32_bf16 v[0:3], v[38:41], v[82:85], v[0:3]
	s_waitcnt vmcnt(10)
	v_mfma_f32_16x16x32_bf16 v[12:15], v[42:45], v[86:89], v[12:15]
	v_mfma_f32_16x16x32_bf16 v[8:11], v[46:49], v[86:89], v[8:11]
	v_mfma_f32_16x16x32_bf16 v[4:7], v[50:53], v[86:89], v[4:7]
	s_waitcnt lgkmcnt(0)
	v_mfma_f32_16x16x32_bf16 v[0:3], v[54:57], v[86:89], v[0:3]
	ds_read_b128 v[34:37], v58 offset:128
	ds_read_b128 v[42:45], v58 offset:192
	s_waitcnt vmcnt(9) lgkmcnt(1)
	v_mfma_f32_16x16x32_bf16 v[12:15], v[34:37], v[90:93], v[12:15]
	ds_read_b128 v[34:37], v58 offset:16768
	ds_read_b128 v[46:49], v58 offset:16832
	s_waitcnt lgkmcnt(1)
	v_mfma_f32_16x16x32_bf16 v[8:11], v[34:37], v[90:93], v[8:11]
	ds_read_b128 v[34:37], v58 offset:33408
	ds_read_b128 v[50:53], v58 offset:33472
	s_waitcnt lgkmcnt(1)
	v_mfma_f32_16x16x32_bf16 v[4:7], v[34:37], v[90:93], v[4:7]
	ds_read_b128 v[34:37], v58 offset:50048
	ds_read_b128 v[54:57], v58 offset:50112
	s_waitcnt lgkmcnt(1)
	v_mfma_f32_16x16x32_bf16 v[0:3], v[34:37], v[90:93], v[0:3]
	s_waitcnt vmcnt(8)
	v_mfma_f32_16x16x32_bf16 v[12:15], v[42:45], v[94:97], v[12:15]
	v_mfma_f32_16x16x32_bf16 v[8:11], v[46:49], v[94:97], v[8:11]
	v_mfma_f32_16x16x32_bf16 v[4:7], v[50:53], v[94:97], v[4:7]
	s_waitcnt lgkmcnt(0)
	v_mfma_f32_16x16x32_bf16 v[0:3], v[54:57], v[94:97], v[0:3]
	v_add_u32_e32 v58, 0x200, v28
	ds_read_b128 v[38:41], v58
	ds_read_b128 v[42:45], v58 offset:64
	s_waitcnt vmcnt(7) lgkmcnt(1)
	v_mfma_f32_16x16x32_bf16 v[12:15], v[38:41], v[110:113], v[12:15]
	ds_read_b128 v[38:41], v58 offset:16640
	ds_read_b128 v[46:49], v58 offset:16704
	s_waitcnt lgkmcnt(1)
	v_mfma_f32_16x16x32_bf16 v[8:11], v[38:41], v[110:113], v[8:11]
	ds_read_b128 v[38:41], v58 offset:33280
	ds_read_b128 v[50:53], v58 offset:33344
	s_waitcnt lgkmcnt(1)
	v_mfma_f32_16x16x32_bf16 v[4:7], v[38:41], v[110:113], v[4:7]
	ds_read_b128 v[38:41], v58 offset:49920
	ds_read_b128 v[54:57], v58 offset:49984
	s_waitcnt lgkmcnt(1)
	v_mfma_f32_16x16x32_bf16 v[0:3], v[38:41], v[110:113], v[0:3]
	s_waitcnt vmcnt(6)
	v_mfma_f32_16x16x32_bf16 v[12:15], v[42:45], v[114:117], v[12:15]
	v_mfma_f32_16x16x32_bf16 v[8:11], v[46:49], v[114:117], v[8:11]
	v_mfma_f32_16x16x32_bf16 v[4:7], v[50:53], v[114:117], v[4:7]
	s_waitcnt lgkmcnt(0)
	v_mfma_f32_16x16x32_bf16 v[0:3], v[54:57], v[114:117], v[0:3]
	ds_read_b128 v[34:37], v58 offset:128
	ds_read_b128 v[42:45], v58 offset:192
	s_waitcnt vmcnt(5) lgkmcnt(1)
	v_mfma_f32_16x16x32_bf16 v[12:15], v[34:37], v[122:125], v[12:15]
	ds_read_b128 v[34:37], v58 offset:16768
	ds_read_b128 v[46:49], v58 offset:16832
	s_waitcnt lgkmcnt(1)
	v_mfma_f32_16x16x32_bf16 v[8:11], v[34:37], v[122:125], v[8:11]
	ds_read_b128 v[34:37], v58 offset:33408
	ds_read_b128 v[50:53], v58 offset:33472
	s_waitcnt lgkmcnt(1)
	v_mfma_f32_16x16x32_bf16 v[4:7], v[34:37], v[122:125], v[4:7]
	ds_read_b128 v[34:37], v58 offset:50048
	ds_read_b128 v[54:57], v58 offset:50112
	s_waitcnt lgkmcnt(1)
	v_mfma_f32_16x16x32_bf16 v[0:3], v[34:37], v[122:125], v[0:3]
	s_waitcnt vmcnt(4)
	v_mfma_f32_16x16x32_bf16 v[12:15], v[42:45], v[126:129], v[12:15]
	v_mfma_f32_16x16x32_bf16 v[8:11], v[46:49], v[126:129], v[8:11]
	v_mfma_f32_16x16x32_bf16 v[4:7], v[50:53], v[126:129], v[4:7]
	s_waitcnt lgkmcnt(0)
	v_mfma_f32_16x16x32_bf16 v[0:3], v[54:57], v[126:129], v[0:3]
	v_add_u32_e32 v58, 0x300, v28
	ds_read_b128 v[38:41], v58
	ds_read_b128 v[42:45], v58 offset:64
	s_waitcnt vmcnt(3) lgkmcnt(1)
	v_mfma_f32_16x16x32_bf16 v[12:15], v[38:41], v[130:133], v[12:15]
	ds_read_b128 v[38:41], v58 offset:16640
	ds_read_b128 v[46:49], v58 offset:16704
	s_waitcnt lgkmcnt(1)
	v_mfma_f32_16x16x32_bf16 v[8:11], v[38:41], v[130:133], v[8:11]
	ds_read_b128 v[38:41], v58 offset:33280
	ds_read_b128 v[50:53], v58 offset:33344
	s_waitcnt lgkmcnt(1)
	v_mfma_f32_16x16x32_bf16 v[4:7], v[38:41], v[130:133], v[4:7]
	ds_read_b128 v[38:41], v58 offset:49920
	ds_read_b128 v[54:57], v58 offset:49984
	s_waitcnt lgkmcnt(1)
	v_mfma_f32_16x16x32_bf16 v[0:3], v[38:41], v[130:133], v[0:3]
	s_waitcnt vmcnt(2)
	v_mfma_f32_16x16x32_bf16 v[12:15], v[42:45], v[134:137], v[12:15]
	v_mfma_f32_16x16x32_bf16 v[8:11], v[46:49], v[134:137], v[8:11]
	v_mfma_f32_16x16x32_bf16 v[4:7], v[50:53], v[134:137], v[4:7]
	s_waitcnt lgkmcnt(0)
	v_mfma_f32_16x16x32_bf16 v[0:3], v[54:57], v[134:137], v[0:3]
	ds_read_b128 v[34:37], v58 offset:128
	ds_read_b128 v[42:45], v58 offset:192
	s_waitcnt vmcnt(1) lgkmcnt(1)
	v_mfma_f32_16x16x32_bf16 v[12:15], v[34:37], v[138:141], v[12:15]
	ds_read_b128 v[34:37], v58 offset:16768
	ds_read_b128 v[46:49], v58 offset:16832
	s_waitcnt lgkmcnt(1)
	v_mfma_f32_16x16x32_bf16 v[8:11], v[34:37], v[138:141], v[8:11]
	ds_read_b128 v[34:37], v58 offset:33408
	ds_read_b128 v[50:53], v58 offset:33472
	s_waitcnt lgkmcnt(1)
	v_mfma_f32_16x16x32_bf16 v[4:7], v[34:37], v[138:141], v[4:7]
	ds_read_b128 v[34:37], v58 offset:50048
	ds_read_b128 v[54:57], v58 offset:50112
	s_waitcnt lgkmcnt(1)
	v_mfma_f32_16x16x32_bf16 v[0:3], v[34:37], v[138:141], v[0:3]
	s_waitcnt vmcnt(0)
	v_mfma_f32_16x16x32_bf16 v[12:15], v[42:45], v[60:63], v[12:15]
	v_mfma_f32_16x16x32_bf16 v[8:11], v[46:49], v[60:63], v[8:11]
	v_mfma_f32_16x16x32_bf16 v[4:7], v[50:53], v[60:63], v[4:7]
	s_waitcnt lgkmcnt(0)
	v_mfma_f32_16x16x32_bf16 v[0:3], v[54:57], v[60:63], v[0:3]
	s_nop 0
	v_lshl_or_b32 v26, v16, 4, v181
	v_add_u32_e32 v26, s13, v26
	v_ashrrev_i32_e32 v27, 31, v26
	v_lshlrev_b64 v[26:27], 11, v[26:27]
	v_lshl_add_u64 v[26:27], v[22:23], 0, v[26:27]
	s_nop 1
	v_cvt_pk_bf16_f32 v0, v0, v1
	v_cvt_pk_bf16_f32 v1, v2, v3
	global_store_dwordx2 v[26:27], v[0:1], off offset:96
	v_add_u32_e32 v0, 8, v16
	v_cmp_lt_u32_e32 vcc, 7, v16
	v_cvt_pk_bf16_f32 v12, v12, v13
	v_cvt_pk_bf16_f32 v13, v14, v15
	v_cvt_pk_bf16_f32 v8, v8, v9
	v_cvt_pk_bf16_f32 v9, v10, v11
	v_cvt_pk_bf16_f32 v4, v4, v5
	v_cvt_pk_bf16_f32 v5, v6, v7
	v_lshl_add_u64 v[24:25], v[24:25], 0, s[6:7]
	s_or_b64 s[8:9], vcc, s[8:9]
	v_mov_b32_e32 v16, v0
	global_store_dwordx2 v[26:27], v[12:13], off
	global_store_dwordx2 v[26:27], v[8:9], off offset:32
	global_store_dwordx2 v[26:27], v[4:5], off offset:64
	s_andn2_b64 exec, exec, s[8:9]
	s_cbranch_execnz .LBB0_591
	s_or_b64 exec, exec, s[8:9]
	s_add_i32 s12, s12, s68
	s_cmpk_gt_i32 s12, 0xff
	s_barrier
	s_cbranch_scc0 .LBB0_588
